# v091 + P7 K-loops: the 8 no-op 's_setprio 0; s_setprio N' pairs between the two MFMA groups of each block removed
# baseline (speedup 1.0000x reference)
.LBB0_793:
	ds_read_b128 v[144:147], v153
	ds_read_b128 v[158:161], v153 offset:1024
	ds_read_b128 v[162:165], v153 offset:2048
	ds_read_b128 v[166:169], v153 offset:3072
	ds_read_b128 v[170:173], v154
	ds_read_b128 v[176:179], v154 offset:1024
	ds_read_b128 v[180:183], v154 offset:2048
	ds_read_b128 v[184:187], v154 offset:3072
	s_add_u32 s44, s42, 0xfff80080
	s_addc_u32 s45, s43, -1
	s_cmp_eq_u32 s65, 28
	s_cselect_b32 s47, s35, s45
	s_cselect_b32 s46, s61, s44
	s_cselect_b32 s45, s27, s64
	s_cselect_b32 s44, s62, s63
	s_add_u32 s100, s46, 0x80
	s_addc_u32 s101, s47, 0
	s_add_i32 m0, s10, 0xc000
	ds_read_b128 v[188:191], v155
	ds_read_b128 v[192:195], v155 offset:1024
	ds_read_b128 v[196:199], v155 offset:2048
	ds_read_b128 v[200:203], v155 offset:3072
	ds_read_b128 v[204:207], v155 offset:4096
	ds_read_b128 v[208:211], v155 offset:5120
	ds_read_b128 v[212:215], v155 offset:6144
	ds_read_b128 v[216:219], v155 offset:7168
	global_load_lds_dwordx4 v136, s[42:43]
	s_add_i32 m0, s10, 0xe000
	s_nop 0
	global_load_lds_dwordx4 v138, s[42:43]
	s_waitcnt vmcnt(8)
	s_waitcnt lgkmcnt(0)
	s_setprio 1
	s_waitcnt lgkmcnt(0)
	v_mfma_f32_16x16x32_bf16 v[124:127], v[144:147], v[188:191], v[124:127]
	v_mfma_f32_16x16x32_bf16 v[124:127], v[158:161], v[192:195], v[124:127]
	v_mfma_f32_16x16x32_bf16 v[120:123], v[166:169], v[192:195], v[120:123]
	v_mfma_f32_16x16x32_bf16 v[120:123], v[162:165], v[188:191], v[120:123]
	v_mfma_f32_16x16x32_bf16 v[104:107], v[162:165], v[196:199], v[104:107]
	v_mfma_f32_16x16x32_bf16 v[104:107], v[166:169], v[200:203], v[104:107]
	v_mfma_f32_16x16x32_bf16 v[108:111], v[158:161], v[200:203], v[108:111]
	v_mfma_f32_16x16x32_bf16 v[108:111], v[144:147], v[196:199], v[108:111]
	v_mfma_f32_16x16x32_bf16 v[92:95], v[144:147], v[204:207], v[92:95]
	v_mfma_f32_16x16x32_bf16 v[92:95], v[158:161], v[208:211], v[92:95]
	v_mfma_f32_16x16x32_bf16 v[88:91], v[166:169], v[208:211], v[88:91]
	v_mfma_f32_16x16x32_bf16 v[88:91], v[162:165], v[204:207], v[88:91]
	v_mfma_f32_16x16x32_bf16 v[72:75], v[162:165], v[212:215], v[72:75]
	v_mfma_f32_16x16x32_bf16 v[72:75], v[166:169], v[216:219], v[72:75]
	v_mfma_f32_16x16x32_bf16 v[76:79], v[158:161], v[216:219], v[76:79]
	v_mfma_f32_16x16x32_bf16 v[76:79], v[144:147], v[212:215], v[76:79]
	v_mfma_f32_16x16x32_bf16 v[116:119], v[170:173], v[188:191], v[116:119]
	v_mfma_f32_16x16x32_bf16 v[116:119], v[176:179], v[192:195], v[116:119]
	v_mfma_f32_16x16x32_bf16 v[112:115], v[184:187], v[192:195], v[112:115]
	v_mfma_f32_16x16x32_bf16 v[112:115], v[180:183], v[188:191], v[112:115]
	v_mfma_f32_16x16x32_bf16 v[96:99], v[180:183], v[196:199], v[96:99]
	v_mfma_f32_16x16x32_bf16 v[96:99], v[184:187], v[200:203], v[96:99]
	v_mfma_f32_16x16x32_bf16 v[100:103], v[176:179], v[200:203], v[100:103]
	v_mfma_f32_16x16x32_bf16 v[100:103], v[170:173], v[196:199], v[100:103]
	v_mfma_f32_16x16x32_bf16 v[84:87], v[170:173], v[204:207], v[84:87]
	v_mfma_f32_16x16x32_bf16 v[84:87], v[176:179], v[208:211], v[84:87]
	v_mfma_f32_16x16x32_bf16 v[80:83], v[184:187], v[208:211], v[80:83]
	v_mfma_f32_16x16x32_bf16 v[80:83], v[180:183], v[204:207], v[80:83]
	v_mfma_f32_16x16x32_bf16 v[64:67], v[180:183], v[212:215], v[64:67]
	v_mfma_f32_16x16x32_bf16 v[64:67], v[184:187], v[216:219], v[64:67]
	v_mfma_f32_16x16x32_bf16 v[68:71], v[176:179], v[216:219], v[68:71]
	v_mfma_f32_16x16x32_bf16 v[68:71], v[170:173], v[212:215], v[68:71]
	s_setprio 0
	s_barrier
	s_add_i32 s66, s49, s0
	s_mov_b32 m0, s66
	ds_read_b128 v[188:191], v155 offset:16384
	ds_read_b128 v[192:195], v155 offset:17408
	ds_read_b128 v[196:199], v155 offset:18432
	ds_read_b128 v[200:203], v155 offset:19456
	ds_read_b128 v[204:207], v155 offset:20480
	ds_read_b128 v[208:211], v155 offset:21504
	ds_read_b128 v[212:215], v155 offset:22528
	ds_read_b128 v[216:219], v155 offset:23552
	global_load_lds_dwordx4 v132, s[44:45]
	s_add_i32 m0, s66, 0x2000
	s_add_u32 s66, s44, 0x80000
	s_addc_u32 s67, s45, 0
	s_add_i32 s68, s50, s0
	global_load_lds_dwordx4 v128, s[44:45]
	s_mov_b32 m0, s68
	s_nop 0
	global_load_lds_dwordx4 v132, s[66:67]
	s_add_i32 m0, s68, 0x2000
	s_nop 0
	global_load_lds_dwordx4 v128, s[66:67]
	s_mov_b32 m0, s10
	s_nop 0
	global_load_lds_dwordx4 v134, s[46:47]
	s_mov_b32 m0, s11
	s_nop 0
	global_load_lds_dwordx4 v130, s[46:47]
	s_waitcnt vmcnt(8)
	s_waitcnt lgkmcnt(0)
	s_setprio 1
	s_waitcnt lgkmcnt(0)
	v_mfma_f32_16x16x32_bf16 v[60:63], v[144:147], v[188:191], v[60:63]
	v_mfma_f32_16x16x32_bf16 v[60:63], v[158:161], v[192:195], v[60:63]
	v_mfma_f32_16x16x32_bf16 v[56:59], v[166:169], v[192:195], v[56:59]
	v_mfma_f32_16x16x32_bf16 v[56:59], v[162:165], v[188:191], v[56:59]
	v_mfma_f32_16x16x32_bf16 v[40:43], v[162:165], v[196:199], v[40:43]
	v_mfma_f32_16x16x32_bf16 v[40:43], v[166:169], v[200:203], v[40:43]
	v_mfma_f32_16x16x32_bf16 v[44:47], v[158:161], v[200:203], v[44:47]
	v_mfma_f32_16x16x32_bf16 v[44:47], v[144:147], v[196:199], v[44:47]
	v_mfma_f32_16x16x32_bf16 v[28:31], v[144:147], v[204:207], v[28:31]
	v_mfma_f32_16x16x32_bf16 v[28:31], v[158:161], v[208:211], v[28:31]
	v_mfma_f32_16x16x32_bf16 v[24:27], v[166:169], v[208:211], v[24:27]
	v_mfma_f32_16x16x32_bf16 v[24:27], v[162:165], v[204:207], v[24:27]
	v_mfma_f32_16x16x32_bf16 v[8:11], v[162:165], v[212:215], v[8:11]
	v_mfma_f32_16x16x32_bf16 v[8:11], v[166:169], v[216:219], v[8:11]
	v_mfma_f32_16x16x32_bf16 v[12:15], v[158:161], v[216:219], v[12:15]
	v_mfma_f32_16x16x32_bf16 v[12:15], v[144:147], v[212:215], v[12:15]
	v_mfma_f32_16x16x32_bf16 v[52:55], v[170:173], v[188:191], v[52:55]
	v_mfma_f32_16x16x32_bf16 v[52:55], v[176:179], v[192:195], v[52:55]
	v_mfma_f32_16x16x32_bf16 v[48:51], v[184:187], v[192:195], v[48:51]
	v_mfma_f32_16x16x32_bf16 v[48:51], v[180:183], v[188:191], v[48:51]
	v_mfma_f32_16x16x32_bf16 v[32:35], v[180:183], v[196:199], v[32:35]
	v_mfma_f32_16x16x32_bf16 v[32:35], v[184:187], v[200:203], v[32:35]
	v_mfma_f32_16x16x32_bf16 v[36:39], v[176:179], v[200:203], v[36:39]
	v_mfma_f32_16x16x32_bf16 v[36:39], v[170:173], v[196:199], v[36:39]
	v_mfma_f32_16x16x32_bf16 v[20:23], v[170:173], v[204:207], v[20:23]
	v_mfma_f32_16x16x32_bf16 v[20:23], v[176:179], v[208:211], v[20:23]
	v_mfma_f32_16x16x32_bf16 v[16:19], v[184:187], v[208:211], v[16:19]
	v_mfma_f32_16x16x32_bf16 v[16:19], v[180:183], v[204:207], v[16:19]
	v_mfma_f32_16x16x32_bf16 v[0:3], v[180:183], v[212:215], v[0:3]
	v_mfma_f32_16x16x32_bf16 v[0:3], v[184:187], v[216:219], v[0:3]
	v_mfma_f32_16x16x32_bf16 v[4:7], v[176:179], v[216:219], v[4:7]
	v_mfma_f32_16x16x32_bf16 v[4:7], v[170:173], v[212:215], v[4:7]
	s_setprio 0
	s_barrier
	s_add_i32 s66, 0, 0x18000
	v_add_u32_e32 v157, s66, v151
	s_add_i32 s67, 0, 0x1c000
	ds_read_b128 v[144:147], v157
	ds_read_b128 v[158:161], v157 offset:1024
	ds_read_b128 v[162:165], v157 offset:2048
	ds_read_b128 v[166:169], v157 offset:3072
	v_add_u32_e32 v157, s67, v151
	ds_read_b128 v[170:173], v157
	ds_read_b128 v[176:179], v157 offset:1024
	ds_read_b128 v[180:183], v157 offset:2048
	ds_read_b128 v[184:187], v157 offset:3072
	s_add_u32 s46, s46, 0x80000
	s_addc_u32 s47, s47, 0
	s_mov_b32 m0, s14
	ds_read_b128 v[188:191], v155 offset:32768
	ds_read_b128 v[192:195], v155 offset:33792
	ds_read_b128 v[196:199], v155 offset:34816
	ds_read_b128 v[200:203], v155 offset:35840
	ds_read_b128 v[204:207], v155 offset:36864
	ds_read_b128 v[208:211], v155 offset:37888
	ds_read_b128 v[212:215], v155 offset:38912
	ds_read_b128 v[216:219], v155 offset:39936
	global_load_lds_dwordx4 v134, s[46:47]
	s_mov_b32 m0, s15
	s_nop 0
	global_load_lds_dwordx4 v130, s[46:47]
	s_waitcnt vmcnt(8)
	s_waitcnt lgkmcnt(0)
	s_setprio 1
	s_waitcnt lgkmcnt(0)
	v_mfma_f32_16x16x32_bf16 v[124:127], v[144:147], v[188:191], v[124:127]
	v_mfma_f32_16x16x32_bf16 v[124:127], v[158:161], v[192:195], v[124:127]
	v_mfma_f32_16x16x32_bf16 v[120:123], v[166:169], v[192:195], v[120:123]
	v_mfma_f32_16x16x32_bf16 v[120:123], v[162:165], v[188:191], v[120:123]
	v_mfma_f32_16x16x32_bf16 v[104:107], v[162:165], v[196:199], v[104:107]
	v_mfma_f32_16x16x32_bf16 v[104:107], v[166:169], v[200:203], v[104:107]
	v_mfma_f32_16x16x32_bf16 v[108:111], v[158:161], v[200:203], v[108:111]
	v_mfma_f32_16x16x32_bf16 v[108:111], v[144:147], v[196:199], v[108:111]
	v_mfma_f32_16x16x32_bf16 v[92:95], v[144:147], v[204:207], v[92:95]
	v_mfma_f32_16x16x32_bf16 v[92:95], v[158:161], v[208:211], v[92:95]
	v_mfma_f32_16x16x32_bf16 v[88:91], v[166:169], v[208:211], v[88:91]
	v_mfma_f32_16x16x32_bf16 v[88:91], v[162:165], v[204:207], v[88:91]
	v_mfma_f32_16x16x32_bf16 v[72:75], v[162:165], v[212:215], v[72:75]
	v_mfma_f32_16x16x32_bf16 v[72:75], v[166:169], v[216:219], v[72:75]
	v_mfma_f32_16x16x32_bf16 v[76:79], v[158:161], v[216:219], v[76:79]
	v_mfma_f32_16x16x32_bf16 v[76:79], v[144:147], v[212:215], v[76:79]
	v_mfma_f32_16x16x32_bf16 v[116:119], v[170:173], v[188:191], v[116:119]
	v_mfma_f32_16x16x32_bf16 v[116:119], v[176:179], v[192:195], v[116:119]
	v_mfma_f32_16x16x32_bf16 v[112:115], v[184:187], v[192:195], v[112:115]
	v_mfma_f32_16x16x32_bf16 v[112:115], v[180:183], v[188:191], v[112:115]
	v_mfma_f32_16x16x32_bf16 v[96:99], v[180:183], v[196:199], v[96:99]
	v_mfma_f32_16x16x32_bf16 v[96:99], v[184:187], v[200:203], v[96:99]
	v_mfma_f32_16x16x32_bf16 v[100:103], v[176:179], v[200:203], v[100:103]
	v_mfma_f32_16x16x32_bf16 v[100:103], v[170:173], v[196:199], v[100:103]
	v_mfma_f32_16x16x32_bf16 v[84:87], v[170:173], v[204:207], v[84:87]
	v_mfma_f32_16x16x32_bf16 v[84:87], v[176:179], v[208:211], v[84:87]
	v_mfma_f32_16x16x32_bf16 v[80:83], v[184:187], v[208:211], v[80:83]
	v_mfma_f32_16x16x32_bf16 v[80:83], v[180:183], v[204:207], v[80:83]
	v_mfma_f32_16x16x32_bf16 v[64:67], v[180:183], v[212:215], v[64:67]
	v_mfma_f32_16x16x32_bf16 v[64:67], v[184:187], v[216:219], v[64:67]
	v_mfma_f32_16x16x32_bf16 v[68:71], v[176:179], v[216:219], v[68:71]
	v_mfma_f32_16x16x32_bf16 v[68:71], v[170:173], v[212:215], v[68:71]
	s_setprio 0
	s_barrier
	s_add_i32 s46, s66, s0
	s_add_u32 s98, s44, 0x80
	s_addc_u32 s99, s45, 0
	s_mov_b32 m0, s46
	ds_read_b128 v[188:191], v155 offset:49152
	ds_read_b128 v[192:195], v155 offset:50176
	ds_read_b128 v[196:199], v155 offset:51200
	ds_read_b128 v[200:203], v155 offset:52224
	ds_read_b128 v[204:207], v155 offset:53248
	ds_read_b128 v[208:211], v155 offset:54272
	ds_read_b128 v[212:215], v155 offset:55296
	ds_read_b128 v[216:219], v155 offset:56320
	global_load_lds_dwordx4 v132, s[98:99]
	s_add_i32 m0, s46, 0x2000
	s_add_u32 s44, s44, 0x80080
	s_addc_u32 s45, s45, 0
	s_add_i32 s46, s67, s0
	global_load_lds_dwordx4 v128, s[98:99]
	s_mov_b32 m0, s46
	s_nop 0
	global_load_lds_dwordx4 v132, s[44:45]
	s_add_i32 m0, s46, 0x2000
	s_nop 0
	global_load_lds_dwordx4 v128, s[44:45]
	s_mov_b32 m0, s41
	s_nop 0
	global_load_lds_dwordx4 v134, s[100:101]
	s_mov_b32 m0, s48
	s_nop 0
	global_load_lds_dwordx4 v130, s[100:101]
	s_waitcnt vmcnt(8)
	s_waitcnt lgkmcnt(0)
	s_setprio 1
	s_waitcnt lgkmcnt(0)
	v_mfma_f32_16x16x32_bf16 v[60:63], v[144:147], v[188:191], v[60:63]
	v_mfma_f32_16x16x32_bf16 v[60:63], v[158:161], v[192:195], v[60:63]
	v_mfma_f32_16x16x32_bf16 v[56:59], v[166:169], v[192:195], v[56:59]
	v_mfma_f32_16x16x32_bf16 v[56:59], v[162:165], v[188:191], v[56:59]
	v_mfma_f32_16x16x32_bf16 v[40:43], v[162:165], v[196:199], v[40:43]
	v_mfma_f32_16x16x32_bf16 v[40:43], v[166:169], v[200:203], v[40:43]
	v_mfma_f32_16x16x32_bf16 v[44:47], v[158:161], v[200:203], v[44:47]
	v_mfma_f32_16x16x32_bf16 v[44:47], v[144:147], v[196:199], v[44:47]
	v_mfma_f32_16x16x32_bf16 v[28:31], v[144:147], v[204:207], v[28:31]
	v_mfma_f32_16x16x32_bf16 v[28:31], v[158:161], v[208:211], v[28:31]
	v_mfma_f32_16x16x32_bf16 v[24:27], v[166:169], v[208:211], v[24:27]
	v_mfma_f32_16x16x32_bf16 v[24:27], v[162:165], v[204:207], v[24:27]
	v_mfma_f32_16x16x32_bf16 v[8:11], v[162:165], v[212:215], v[8:11]
	v_mfma_f32_16x16x32_bf16 v[8:11], v[166:169], v[216:219], v[8:11]
	v_mfma_f32_16x16x32_bf16 v[12:15], v[158:161], v[216:219], v[12:15]
	v_mfma_f32_16x16x32_bf16 v[12:15], v[144:147], v[212:215], v[12:15]
	v_mfma_f32_16x16x32_bf16 v[52:55], v[170:173], v[188:191], v[52:55]
	v_mfma_f32_16x16x32_bf16 v[52:55], v[176:179], v[192:195], v[52:55]
	v_mfma_f32_16x16x32_bf16 v[48:51], v[184:187], v[192:195], v[48:51]
	v_mfma_f32_16x16x32_bf16 v[48:51], v[180:183], v[188:191], v[48:51]
	v_mfma_f32_16x16x32_bf16 v[32:35], v[180:183], v[196:199], v[32:35]
	v_mfma_f32_16x16x32_bf16 v[32:35], v[184:187], v[200:203], v[32:35]
	v_mfma_f32_16x16x32_bf16 v[36:39], v[176:179], v[200:203], v[36:39]
	v_mfma_f32_16x16x32_bf16 v[36:39], v[170:173], v[196:199], v[36:39]
	v_mfma_f32_16x16x32_bf16 v[20:23], v[170:173], v[204:207], v[20:23]
	v_mfma_f32_16x16x32_bf16 v[20:23], v[176:179], v[208:211], v[20:23]
	v_mfma_f32_16x16x32_bf16 v[16:19], v[184:187], v[208:211], v[16:19]
	v_mfma_f32_16x16x32_bf16 v[16:19], v[180:183], v[204:207], v[16:19]
	v_mfma_f32_16x16x32_bf16 v[0:3], v[180:183], v[212:215], v[0:3]
	v_mfma_f32_16x16x32_bf16 v[0:3], v[184:187], v[216:219], v[0:3]
	v_mfma_f32_16x16x32_bf16 v[4:7], v[176:179], v[216:219], v[4:7]
	v_mfma_f32_16x16x32_bf16 v[4:7], v[170:173], v[212:215], v[4:7]
	s_setprio 0
	s_barrier
	s_add_i32 s65, s65, 2
	s_add_u32 s42, s42, 0x100
	s_addc_u32 s43, s43, 0
	s_add_u32 s63, s63, 0x100
	s_addc_u32 s64, s64, 0
	s_cmp_gt_u32 s65, 29
	s_cbranch_scc0 .LBB0_793
	s_branch .Lp7_kloop_done
.Lp7_kloop_h1:
	ds_read_b128 v[144:147], v153
	ds_read_b128 v[158:161], v153 offset:1024
	ds_read_b128 v[162:165], v153 offset:2048
	ds_read_b128 v[166:169], v153 offset:3072
	ds_read_b128 v[170:173], v154
	ds_read_b128 v[176:179], v154 offset:1024
	ds_read_b128 v[180:183], v154 offset:2048
	ds_read_b128 v[184:187], v154 offset:3072
	s_add_u32 s44, s42, 0xfff80080
	s_addc_u32 s45, s43, -1
	s_cmp_eq_u32 s65, 28
	s_cselect_b32 s47, s35, s45
	s_cselect_b32 s46, s61, s44
	s_cselect_b32 s45, s27, s64
	s_cselect_b32 s44, s62, s63
	s_add_u32 s100, s46, 0x80
	s_addc_u32 s101, s47, 0
	s_add_i32 m0, s10, 0xc000
	ds_read_b128 v[188:191], v155
	ds_read_b128 v[192:195], v155 offset:1024
	ds_read_b128 v[196:199], v155 offset:2048
	ds_read_b128 v[200:203], v155 offset:3072
	ds_read_b128 v[204:207], v155 offset:4096
	ds_read_b128 v[208:211], v155 offset:5120
	ds_read_b128 v[212:215], v155 offset:6144
	ds_read_b128 v[216:219], v155 offset:7168
	global_load_lds_dwordx4 v136, s[42:43]
	s_add_i32 m0, s10, 0xe000
	s_nop 0
	global_load_lds_dwordx4 v138, s[42:43]
	s_waitcnt vmcnt(8)
	s_waitcnt lgkmcnt(0)
	s_barrier
	s_setprio 2
	s_waitcnt lgkmcnt(0)
	v_mfma_f32_16x16x32_bf16 v[124:127], v[144:147], v[188:191], v[124:127]
	v_mfma_f32_16x16x32_bf16 v[120:123], v[162:165], v[188:191], v[120:123]
	v_mfma_f32_16x16x32_bf16 v[104:107], v[162:165], v[196:199], v[104:107]
	v_mfma_f32_16x16x32_bf16 v[108:111], v[144:147], v[196:199], v[108:111]
	v_mfma_f32_16x16x32_bf16 v[92:95], v[144:147], v[204:207], v[92:95]
	v_mfma_f32_16x16x32_bf16 v[88:91], v[162:165], v[204:207], v[88:91]
	v_mfma_f32_16x16x32_bf16 v[72:75], v[162:165], v[212:215], v[72:75]
	v_mfma_f32_16x16x32_bf16 v[76:79], v[144:147], v[212:215], v[76:79]
	v_mfma_f32_16x16x32_bf16 v[76:79], v[158:161], v[216:219], v[76:79]
	v_mfma_f32_16x16x32_bf16 v[72:75], v[166:169], v[216:219], v[72:75]
	v_mfma_f32_16x16x32_bf16 v[88:91], v[166:169], v[208:211], v[88:91]
	v_mfma_f32_16x16x32_bf16 v[92:95], v[158:161], v[208:211], v[92:95]
	v_mfma_f32_16x16x32_bf16 v[108:111], v[158:161], v[200:203], v[108:111]
	v_mfma_f32_16x16x32_bf16 v[104:107], v[166:169], v[200:203], v[104:107]
	v_mfma_f32_16x16x32_bf16 v[120:123], v[166:169], v[192:195], v[120:123]
	v_mfma_f32_16x16x32_bf16 v[124:127], v[158:161], v[192:195], v[124:127]
	v_mfma_f32_16x16x32_bf16 v[116:119], v[170:173], v[188:191], v[116:119]
	v_mfma_f32_16x16x32_bf16 v[112:115], v[180:183], v[188:191], v[112:115]
	v_mfma_f32_16x16x32_bf16 v[96:99], v[180:183], v[196:199], v[96:99]
	v_mfma_f32_16x16x32_bf16 v[100:103], v[170:173], v[196:199], v[100:103]
	v_mfma_f32_16x16x32_bf16 v[84:87], v[170:173], v[204:207], v[84:87]
	v_mfma_f32_16x16x32_bf16 v[80:83], v[180:183], v[204:207], v[80:83]
	v_mfma_f32_16x16x32_bf16 v[64:67], v[180:183], v[212:215], v[64:67]
	v_mfma_f32_16x16x32_bf16 v[68:71], v[170:173], v[212:215], v[68:71]
	v_mfma_f32_16x16x32_bf16 v[68:71], v[176:179], v[216:219], v[68:71]
	v_mfma_f32_16x16x32_bf16 v[64:67], v[184:187], v[216:219], v[64:67]
	v_mfma_f32_16x16x32_bf16 v[80:83], v[184:187], v[208:211], v[80:83]
	v_mfma_f32_16x16x32_bf16 v[84:87], v[176:179], v[208:211], v[84:87]
	v_mfma_f32_16x16x32_bf16 v[100:103], v[176:179], v[200:203], v[100:103]
	v_mfma_f32_16x16x32_bf16 v[96:99], v[184:187], v[200:203], v[96:99]
	v_mfma_f32_16x16x32_bf16 v[112:115], v[184:187], v[192:195], v[112:115]
	v_mfma_f32_16x16x32_bf16 v[116:119], v[176:179], v[192:195], v[116:119]
	s_setprio 0
	s_add_i32 s66, s49, s0
	s_mov_b32 m0, s66
	ds_read_b128 v[188:191], v155 offset:16384
	ds_read_b128 v[192:195], v155 offset:17408
	ds_read_b128 v[196:199], v155 offset:18432
	ds_read_b128 v[200:203], v155 offset:19456
	ds_read_b128 v[204:207], v155 offset:20480
	ds_read_b128 v[208:211], v155 offset:21504
	ds_read_b128 v[212:215], v155 offset:22528
	ds_read_b128 v[216:219], v155 offset:23552
	global_load_lds_dwordx4 v132, s[44:45]
	s_add_i32 m0, s66, 0x2000
	s_add_u32 s66, s44, 0x80000
	s_addc_u32 s67, s45, 0
	s_add_i32 s68, s50, s0
	global_load_lds_dwordx4 v128, s[44:45]
	s_mov_b32 m0, s68
	s_nop 0
	global_load_lds_dwordx4 v132, s[66:67]
	s_add_i32 m0, s68, 0x2000
	s_nop 0
	global_load_lds_dwordx4 v128, s[66:67]
	s_mov_b32 m0, s10
	s_nop 0
	global_load_lds_dwordx4 v134, s[46:47]
	s_mov_b32 m0, s11
	s_nop 0
	global_load_lds_dwordx4 v130, s[46:47]
	s_waitcnt vmcnt(8)
	s_waitcnt lgkmcnt(0)
	s_barrier
	s_setprio 2
	s_waitcnt lgkmcnt(0)
	v_mfma_f32_16x16x32_bf16 v[60:63], v[144:147], v[188:191], v[60:63]
	v_mfma_f32_16x16x32_bf16 v[56:59], v[162:165], v[188:191], v[56:59]
	v_mfma_f32_16x16x32_bf16 v[40:43], v[162:165], v[196:199], v[40:43]
	v_mfma_f32_16x16x32_bf16 v[44:47], v[144:147], v[196:199], v[44:47]
	v_mfma_f32_16x16x32_bf16 v[28:31], v[144:147], v[204:207], v[28:31]
	v_mfma_f32_16x16x32_bf16 v[24:27], v[162:165], v[204:207], v[24:27]
	v_mfma_f32_16x16x32_bf16 v[8:11], v[162:165], v[212:215], v[8:11]
	v_mfma_f32_16x16x32_bf16 v[12:15], v[144:147], v[212:215], v[12:15]
	v_mfma_f32_16x16x32_bf16 v[12:15], v[158:161], v[216:219], v[12:15]
	v_mfma_f32_16x16x32_bf16 v[8:11], v[166:169], v[216:219], v[8:11]
	v_mfma_f32_16x16x32_bf16 v[24:27], v[166:169], v[208:211], v[24:27]
	v_mfma_f32_16x16x32_bf16 v[28:31], v[158:161], v[208:211], v[28:31]
	v_mfma_f32_16x16x32_bf16 v[44:47], v[158:161], v[200:203], v[44:47]
	v_mfma_f32_16x16x32_bf16 v[40:43], v[166:169], v[200:203], v[40:43]
	v_mfma_f32_16x16x32_bf16 v[56:59], v[166:169], v[192:195], v[56:59]
	v_mfma_f32_16x16x32_bf16 v[60:63], v[158:161], v[192:195], v[60:63]
	v_mfma_f32_16x16x32_bf16 v[52:55], v[170:173], v[188:191], v[52:55]
	v_mfma_f32_16x16x32_bf16 v[48:51], v[180:183], v[188:191], v[48:51]
	v_mfma_f32_16x16x32_bf16 v[32:35], v[180:183], v[196:199], v[32:35]
	v_mfma_f32_16x16x32_bf16 v[36:39], v[170:173], v[196:199], v[36:39]
	v_mfma_f32_16x16x32_bf16 v[20:23], v[170:173], v[204:207], v[20:23]
	v_mfma_f32_16x16x32_bf16 v[16:19], v[180:183], v[204:207], v[16:19]
	v_mfma_f32_16x16x32_bf16 v[0:3], v[180:183], v[212:215], v[0:3]
	v_mfma_f32_16x16x32_bf16 v[4:7], v[170:173], v[212:215], v[4:7]
	v_mfma_f32_16x16x32_bf16 v[4:7], v[176:179], v[216:219], v[4:7]
	v_mfma_f32_16x16x32_bf16 v[0:3], v[184:187], v[216:219], v[0:3]
	v_mfma_f32_16x16x32_bf16 v[16:19], v[184:187], v[208:211], v[16:19]
	v_mfma_f32_16x16x32_bf16 v[20:23], v[176:179], v[208:211], v[20:23]
	v_mfma_f32_16x16x32_bf16 v[36:39], v[176:179], v[200:203], v[36:39]
	v_mfma_f32_16x16x32_bf16 v[32:35], v[184:187], v[200:203], v[32:35]
	v_mfma_f32_16x16x32_bf16 v[48:51], v[184:187], v[192:195], v[48:51]
	v_mfma_f32_16x16x32_bf16 v[52:55], v[176:179], v[192:195], v[52:55]
	s_setprio 0
	s_add_i32 s66, 0, 0x18000
	v_add_u32_e32 v157, s66, v151
	s_add_i32 s67, 0, 0x1c000
	ds_read_b128 v[144:147], v157
	ds_read_b128 v[158:161], v157 offset:1024
	ds_read_b128 v[162:165], v157 offset:2048
	ds_read_b128 v[166:169], v157 offset:3072
	v_add_u32_e32 v157, s67, v151
	ds_read_b128 v[170:173], v157
	ds_read_b128 v[176:179], v157 offset:1024
	ds_read_b128 v[180:183], v157 offset:2048
	ds_read_b128 v[184:187], v157 offset:3072
	s_add_u32 s46, s46, 0x80000
	s_addc_u32 s47, s47, 0
	s_mov_b32 m0, s14
	ds_read_b128 v[188:191], v155 offset:32768
	ds_read_b128 v[192:195], v155 offset:33792
	ds_read_b128 v[196:199], v155 offset:34816
	ds_read_b128 v[200:203], v155 offset:35840
	ds_read_b128 v[204:207], v155 offset:36864
	ds_read_b128 v[208:211], v155 offset:37888
	ds_read_b128 v[212:215], v155 offset:38912
	ds_read_b128 v[216:219], v155 offset:39936
	global_load_lds_dwordx4 v134, s[46:47]
	s_mov_b32 m0, s15
	s_nop 0
	global_load_lds_dwordx4 v130, s[46:47]
	s_waitcnt vmcnt(8)
	s_waitcnt lgkmcnt(0)
	s_barrier
	s_setprio 2
	s_waitcnt lgkmcnt(0)
	v_mfma_f32_16x16x32_bf16 v[124:127], v[144:147], v[188:191], v[124:127]
	v_mfma_f32_16x16x32_bf16 v[120:123], v[162:165], v[188:191], v[120:123]
	v_mfma_f32_16x16x32_bf16 v[104:107], v[162:165], v[196:199], v[104:107]
	v_mfma_f32_16x16x32_bf16 v[108:111], v[144:147], v[196:199], v[108:111]
	v_mfma_f32_16x16x32_bf16 v[92:95], v[144:147], v[204:207], v[92:95]
	v_mfma_f32_16x16x32_bf16 v[88:91], v[162:165], v[204:207], v[88:91]
	v_mfma_f32_16x16x32_bf16 v[72:75], v[162:165], v[212:215], v[72:75]
	v_mfma_f32_16x16x32_bf16 v[76:79], v[144:147], v[212:215], v[76:79]
	v_mfma_f32_16x16x32_bf16 v[76:79], v[158:161], v[216:219], v[76:79]
	v_mfma_f32_16x16x32_bf16 v[72:75], v[166:169], v[216:219], v[72:75]
	v_mfma_f32_16x16x32_bf16 v[88:91], v[166:169], v[208:211], v[88:91]
	v_mfma_f32_16x16x32_bf16 v[92:95], v[158:161], v[208:211], v[92:95]
	v_mfma_f32_16x16x32_bf16 v[108:111], v[158:161], v[200:203], v[108:111]
	v_mfma_f32_16x16x32_bf16 v[104:107], v[166:169], v[200:203], v[104:107]
	v_mfma_f32_16x16x32_bf16 v[120:123], v[166:169], v[192:195], v[120:123]
	v_mfma_f32_16x16x32_bf16 v[124:127], v[158:161], v[192:195], v[124:127]
	v_mfma_f32_16x16x32_bf16 v[116:119], v[170:173], v[188:191], v[116:119]
	v_mfma_f32_16x16x32_bf16 v[112:115], v[180:183], v[188:191], v[112:115]
	v_mfma_f32_16x16x32_bf16 v[96:99], v[180:183], v[196:199], v[96:99]
	v_mfma_f32_16x16x32_bf16 v[100:103], v[170:173], v[196:199], v[100:103]
	v_mfma_f32_16x16x32_bf16 v[84:87], v[170:173], v[204:207], v[84:87]
	v_mfma_f32_16x16x32_bf16 v[80:83], v[180:183], v[204:207], v[80:83]
	v_mfma_f32_16x16x32_bf16 v[64:67], v[180:183], v[212:215], v[64:67]
	v_mfma_f32_16x16x32_bf16 v[68:71], v[170:173], v[212:215], v[68:71]
	v_mfma_f32_16x16x32_bf16 v[68:71], v[176:179], v[216:219], v[68:71]
	v_mfma_f32_16x16x32_bf16 v[64:67], v[184:187], v[216:219], v[64:67]
	v_mfma_f32_16x16x32_bf16 v[80:83], v[184:187], v[208:211], v[80:83]
	v_mfma_f32_16x16x32_bf16 v[84:87], v[176:179], v[208:211], v[84:87]
	v_mfma_f32_16x16x32_bf16 v[100:103], v[176:179], v[200:203], v[100:103]
	v_mfma_f32_16x16x32_bf16 v[96:99], v[184:187], v[200:203], v[96:99]
	v_mfma_f32_16x16x32_bf16 v[112:115], v[184:187], v[192:195], v[112:115]
	v_mfma_f32_16x16x32_bf16 v[116:119], v[176:179], v[192:195], v[116:119]
	s_setprio 0
	s_add_i32 s46, s66, s0
	s_add_u32 s98, s44, 0x80
	s_addc_u32 s99, s45, 0
	s_mov_b32 m0, s46
	ds_read_b128 v[188:191], v155 offset:49152
	ds_read_b128 v[192:195], v155 offset:50176
	ds_read_b128 v[196:199], v155 offset:51200
	ds_read_b128 v[200:203], v155 offset:52224
	ds_read_b128 v[204:207], v155 offset:53248
	ds_read_b128 v[208:211], v155 offset:54272
	ds_read_b128 v[212:215], v155 offset:55296
	ds_read_b128 v[216:219], v155 offset:56320
	global_load_lds_dwordx4 v132, s[98:99]
	s_add_i32 m0, s46, 0x2000
	s_add_u32 s44, s44, 0x80080
	s_addc_u32 s45, s45, 0
	s_add_i32 s46, s67, s0
	global_load_lds_dwordx4 v128, s[98:99]
	s_mov_b32 m0, s46
	s_nop 0
	global_load_lds_dwordx4 v132, s[44:45]
	s_add_i32 m0, s46, 0x2000
	s_nop 0
	global_load_lds_dwordx4 v128, s[44:45]
	s_mov_b32 m0, s41
	s_nop 0
	global_load_lds_dwordx4 v134, s[100:101]
	s_mov_b32 m0, s48
	s_nop 0
	global_load_lds_dwordx4 v130, s[100:101]
	s_waitcnt vmcnt(8)
	s_waitcnt lgkmcnt(0)
	s_barrier
	s_setprio 2
	s_waitcnt lgkmcnt(0)
	v_mfma_f32_16x16x32_bf16 v[60:63], v[144:147], v[188:191], v[60:63]
	v_mfma_f32_16x16x32_bf16 v[56:59], v[162:165], v[188:191], v[56:59]
	v_mfma_f32_16x16x32_bf16 v[40:43], v[162:165], v[196:199], v[40:43]
	v_mfma_f32_16x16x32_bf16 v[44:47], v[144:147], v[196:199], v[44:47]
	v_mfma_f32_16x16x32_bf16 v[28:31], v[144:147], v[204:207], v[28:31]
	v_mfma_f32_16x16x32_bf16 v[24:27], v[162:165], v[204:207], v[24:27]
	v_mfma_f32_16x16x32_bf16 v[8:11], v[162:165], v[212:215], v[8:11]
	v_mfma_f32_16x16x32_bf16 v[12:15], v[144:147], v[212:215], v[12:15]
	v_mfma_f32_16x16x32_bf16 v[12:15], v[158:161], v[216:219], v[12:15]
	v_mfma_f32_16x16x32_bf16 v[8:11], v[166:169], v[216:219], v[8:11]
	v_mfma_f32_16x16x32_bf16 v[24:27], v[166:169], v[208:211], v[24:27]
	v_mfma_f32_16x16x32_bf16 v[28:31], v[158:161], v[208:211], v[28:31]
	v_mfma_f32_16x16x32_bf16 v[44:47], v[158:161], v[200:203], v[44:47]
	v_mfma_f32_16x16x32_bf16 v[40:43], v[166:169], v[200:203], v[40:43]
	v_mfma_f32_16x16x32_bf16 v[56:59], v[166:169], v[192:195], v[56:59]
	v_mfma_f32_16x16x32_bf16 v[60:63], v[158:161], v[192:195], v[60:63]
	v_mfma_f32_16x16x32_bf16 v[52:55], v[170:173], v[188:191], v[52:55]
	v_mfma_f32_16x16x32_bf16 v[48:51], v[180:183], v[188:191], v[48:51]
	v_mfma_f32_16x16x32_bf16 v[32:35], v[180:183], v[196:199], v[32:35]
	v_mfma_f32_16x16x32_bf16 v[36:39], v[170:173], v[196:199], v[36:39]
	v_mfma_f32_16x16x32_bf16 v[20:23], v[170:173], v[204:207], v[20:23]
	v_mfma_f32_16x16x32_bf16 v[16:19], v[180:183], v[204:207], v[16:19]
	v_mfma_f32_16x16x32_bf16 v[0:3], v[180:183], v[212:215], v[0:3]
	v_mfma_f32_16x16x32_bf16 v[4:7], v[170:173], v[212:215], v[4:7]
	v_mfma_f32_16x16x32_bf16 v[4:7], v[176:179], v[216:219], v[4:7]
	v_mfma_f32_16x16x32_bf16 v[0:3], v[184:187], v[216:219], v[0:3]
	v_mfma_f32_16x16x32_bf16 v[16:19], v[184:187], v[208:211], v[16:19]
	v_mfma_f32_16x16x32_bf16 v[20:23], v[176:179], v[208:211], v[20:23]
	v_mfma_f32_16x16x32_bf16 v[36:39], v[176:179], v[200:203], v[36:39]
	v_mfma_f32_16x16x32_bf16 v[32:35], v[184:187], v[200:203], v[32:35]
	v_mfma_f32_16x16x32_bf16 v[48:51], v[184:187], v[192:195], v[48:51]
	v_mfma_f32_16x16x32_bf16 v[52:55], v[176:179], v[192:195], v[52:55]
	s_setprio 0
	s_add_i32 s65, s65, 2
	s_add_u32 s42, s42, 0x100
	s_addc_u32 s43, s43, 0
	s_add_u32 s63, s63, 0x100
	s_addc_u32 s64, s64, 0
	s_cmp_gt_u32 s65, 29
	s_cbranch_scc0 .Lp7_kloop_h1
